# stack42 with s_sleep 1 removed from the grid-barrier polling loops (tighter polling)
# baseline (speedup 1.0000x reference)
.LBB0_10:
	global_load_dword v2, v1, s[4:5] offset:32 sc1
	s_waitcnt vmcnt(0)
	v_and_b32_e32 v2, 0xffff0000, v2
	v_cmp_ne_u32_e32 vcc, v2, v0
	s_or_b64 s[6:7], vcc, s[6:7]
	s_andn2_b64 exec, exec, s[6:7]
	s_cbranch_execnz .LBB0_10

.LBB0_98:
	global_load_dword v15, v16, s[12:13] sc1
	global_load_dword v0, v16, s[14:15] sc1
	global_load_dword v1, v16, s[16:17] sc1
	global_load_dword v2, v16, s[18:19] sc1
	global_load_dword v3, v16, s[28:29] sc1
	global_load_dword v4, v16, s[30:31] sc1
	global_load_dword v5, v16, s[34:35] sc1
	global_load_dword v6, v16, s[36:37] sc1
	global_load_dword v7, v16, s[38:39] sc1
	global_load_dword v8, v16, s[40:41] sc1
	global_load_dword v9, v16, s[42:43] sc1
	global_load_dword v10, v16, s[44:45] sc1
	global_load_dword v11, v16, s[46:47] sc1
	global_load_dword v12, v16, s[48:49] sc1
	global_load_dword v13, v16, s[50:51] sc1
	global_load_dword v14, v16, s[52:53] sc1
	s_mov_b64 s[54:55], -1
	s_mov_b64 s[56:57], -1
	s_waitcnt vmcnt(14)
	v_add_u32_e32 v17, v0, v15
	s_waitcnt vmcnt(13)
	v_add_u32_e32 v17, v17, v1
	s_waitcnt vmcnt(12)
	v_add_u32_e32 v17, v17, v2
	s_waitcnt vmcnt(11)
	v_add_u32_e32 v17, v17, v3
	s_waitcnt vmcnt(10)
	v_add_u32_e32 v17, v17, v4
	s_waitcnt vmcnt(9)
	v_add_u32_e32 v17, v17, v5
	s_waitcnt vmcnt(8)
	v_add_u32_e32 v17, v17, v6
	s_waitcnt vmcnt(7)
	v_add_u32_e32 v17, v17, v7
	s_waitcnt vmcnt(6)
	v_add_u32_e32 v17, v17, v8
	s_waitcnt vmcnt(5)
	v_add_u32_e32 v17, v17, v9
	s_waitcnt vmcnt(4)
	v_add_u32_e32 v17, v17, v10
	s_waitcnt vmcnt(3)
	v_add_u32_e32 v17, v17, v11
	s_waitcnt vmcnt(2)
	v_add_u32_e32 v17, v17, v12
	s_waitcnt vmcnt(1)
	v_add_u32_e32 v17, v17, v13
	s_waitcnt vmcnt(0)
	v_add_u32_e32 v17, v17, v14
	v_cmp_eq_u32_e32 vcc, s21, v17
	s_cbranch_vccnz .LBB0_97
	s_and_b32 s24, s23, 0xff
	s_cmp_eq_u32 s24, 0
	s_mov_b64 s[58:59], -1
	s_cbranch_scc0 .LBB0_102
	global_load_dword v17, v16, s[8:9] sc1
	s_waitcnt vmcnt(0)
	v_cmp_eq_u32_e32 vcc, 0, v17
	s_cbranch_vccnz .LBB0_104
	s_mov_b64 s[58:59], 0

.LBB0_116:
	s_and_b32 s21, s11, 0xff
	s_mov_b64 s[34:35], -1
	s_cmp_lg_u32 s21, 0
	s_mov_b64 s[38:39], -1
	s_cbranch_scc1 .LBB0_119
	global_load_dword v2, v0, s[16:17] sc1
	s_waitcnt vmcnt(0)
	v_cmp_eq_u32_e32 vcc, 0, v2
	s_cbranch_vccnz .LBB0_121
	s_mov_b64 s[38:39], 0
	s_mov_b64 s[36:37], -1

.LBB0_133:
	s_and_b32 s21, s11, 0xff
	s_cmp_lg_u32 s21, 0
	s_mov_b64 s[34:35], -1
	s_cbranch_scc1 .LBB0_136
	global_load_dword v1, v0, s[16:17] sc1
	s_waitcnt vmcnt(0)
	v_cmp_eq_u32_e32 vcc, 0, v1
	s_cbranch_vccnz .LBB0_138
	s_mov_b64 s[34:35], 0
	s_mov_b64 s[30:31], -1

.LBB0_1343:
	global_load_dword v15, v16, s[10:11] sc1
	global_load_dword v0, v16, s[12:13] sc1
	global_load_dword v1, v16, s[14:15] sc1
	global_load_dword v2, v16, s[16:17] sc1
	global_load_dword v3, v16, s[18:19] sc1
	global_load_dword v4, v16, s[26:27] sc1
	global_load_dword v5, v16, s[28:29] sc1
	global_load_dword v6, v16, s[30:31] sc1
	global_load_dword v7, v16, s[34:35] sc1
	global_load_dword v8, v16, s[36:37] sc1
	global_load_dword v9, v16, s[38:39] sc1
	global_load_dword v10, v16, s[40:41] sc1
	global_load_dword v11, v16, s[42:43] sc1
	global_load_dword v12, v16, s[44:45] sc1
	global_load_dword v13, v16, s[46:47] sc1
	global_load_dword v14, v16, s[48:49] sc1
	s_mov_b64 s[50:51], -1
	s_mov_b64 s[52:53], -1
	s_waitcnt vmcnt(14)
	v_add_u32_e32 v17, v0, v15
	s_waitcnt vmcnt(13)
	v_add_u32_e32 v17, v17, v1
	s_waitcnt vmcnt(12)
	v_add_u32_e32 v17, v17, v2
	s_waitcnt vmcnt(11)
	v_add_u32_e32 v17, v17, v3
	s_waitcnt vmcnt(10)
	v_add_u32_e32 v17, v17, v4
	s_waitcnt vmcnt(9)
	v_add_u32_e32 v17, v17, v5
	s_waitcnt vmcnt(8)
	v_add_u32_e32 v17, v17, v6
	s_waitcnt vmcnt(7)
	v_add_u32_e32 v17, v17, v7
	s_waitcnt vmcnt(6)
	v_add_u32_e32 v17, v17, v8
	s_waitcnt vmcnt(5)
	v_add_u32_e32 v17, v17, v9
	s_waitcnt vmcnt(4)
	v_add_u32_e32 v17, v17, v10
	s_waitcnt vmcnt(3)
	v_add_u32_e32 v17, v17, v11
	s_waitcnt vmcnt(2)
	v_add_u32_e32 v17, v17, v12
	s_waitcnt vmcnt(1)
	v_add_u32_e32 v17, v17, v13
	s_waitcnt vmcnt(0)
	v_add_u32_e32 v17, v17, v14
	v_cmp_eq_u32_e32 vcc, s23, v17
	s_cbranch_vccnz .LBB0_1342
	s_and_b32 s25, s24, 0xff
	s_cmp_eq_u32 s25, 0
	s_mov_b64 s[54:55], -1
	s_cbranch_scc0 .LBB0_1347
	global_load_dword v17, v16, s[8:9] sc1
	s_waitcnt vmcnt(0)
	v_cmp_eq_u32_e32 vcc, 0, v17
	s_cbranch_vccnz .LBB0_1349
	s_mov_b64 s[54:55], 0

.LBB0_1361:
	s_and_b32 s23, s21, 0xff
	s_mov_b64 s[28:29], -1
	s_cmp_lg_u32 s23, 0
	s_mov_b64 s[34:35], -1
	s_cbranch_scc1 .LBB0_1364
	global_load_dword v2, v0, s[14:15] sc1
	s_waitcnt vmcnt(0)
	v_cmp_eq_u32_e32 vcc, 0, v2
	s_cbranch_vccnz .LBB0_1366
	s_mov_b64 s[34:35], 0
	s_mov_b64 s[30:31], -1

.LBB0_1378:
	s_and_b32 s23, s21, 0xff
	s_cmp_lg_u32 s23, 0
	s_mov_b64 s[28:29], -1
	s_cbranch_scc1 .LBB0_1381
	global_load_dword v1, v0, s[14:15] sc1
	s_waitcnt vmcnt(0)
	v_cmp_eq_u32_e32 vcc, 0, v1
	s_cbranch_vccnz .LBB0_1383
	s_mov_b64 s[28:29], 0
	s_mov_b64 s[26:27], -1
